# SGU: the 8 W-tile loads and 4 V loads of a unit issued at the unit top together with the row-scale loads
# baseline (speedup 1.0000x reference)
.LBB0_432:
	s_lshr_b32 s33, s89, 1
	v_readlane_b32 s64, v249, 54
	s_add_i32 s33, s33, s64
	s_lshr_b32 s74, s93, 3
	s_and_b64 s[72:73], s[2:3], exec
	s_cselect_b32 s33, s33, s74
	v_readlane_b32 s64, v249, 56
	s_lshl_b32 s33, s33, 7
	v_readlane_b32 s65, v249, 57
	s_and_b32 s98, s89, 1
	s_or_b32 s98, s98, s88
	s_and_b32 s99, s93, 7
	s_and_b64 s[100:101], s[2:3], exec
	s_cselect_b32 s98, s98, s99
	s_lshl_b32 s99, s98, 16
	v_mov_b32_e32 v240, s99
	v_mov_b32_e32 v241, 0
	v_lshl_add_u64 v[240:241], v[114:115], 0, v[240:241]
	v_lshl_add_u64 v[242:243], v[116:117], 2, v[240:241]
	global_load_dwordx4 v[72:75], v[242:243], off
	v_lshl_add_u64 v[242:243], v[122:123], 2, v[240:241]
	global_load_dwordx4 v[76:79], v[242:243], off
	v_lshl_add_u64 v[242:243], v[118:119], 2, v[240:241]
	global_load_dwordx4 v[80:83], v[242:243], off
	v_lshl_add_u64 v[242:243], v[124:125], 2, v[240:241]
	global_load_dwordx4 v[84:87], v[242:243], off
	v_lshl_add_u64 v[242:243], v[120:121], 2, v[240:241]
	global_load_dwordx4 v[88:91], v[242:243], off
	v_lshl_add_u64 v[242:243], v[126:127], 2, v[240:241]
	global_load_dwordx4 v[92:95], v[242:243], off
	v_lshl_add_u64 v[242:243], v[128:129], 2, v[240:241]
	global_load_dwordx4 v[96:99], v[242:243], off
	v_lshl_add_u64 v[242:243], v[130:131], 2, v[240:241]
	global_load_dwordx4 v[100:103], v[242:243], off
	v_or_b32_e32 v244, s33, v141
	v_ashrrev_i32_e32 v245, 31, v244
	v_lshlrev_b64 v[244:245], 12, v[244:245]
	v_lshl_add_u64 v[244:245], s[80:81], 0, v[244:245]
	s_lshl_b32 s99, s98, 8
	v_mov_b32_e32 v246, s99
	v_mov_b32_e32 v247, 0
	v_lshl_add_u64 v[244:245], v[244:245], 0, v[246:247]
	v_lshl_add_u64 v[246:247], v[132:133], 1, v[244:245]
	global_load_dwordx4 v[34:37], v[246:247], off offset:2048
	v_lshl_add_u64 v[246:247], v[134:135], 1, v[244:245]
	global_load_dwordx4 v[38:41], v[246:247], off offset:2048
	v_lshl_add_u64 v[246:247], v[136:137], 1, v[244:245]
	global_load_dwordx4 v[42:45], v[246:247], off offset:2048
	v_lshl_add_u64 v[246:247], v[138:139], 1, v[244:245]
	global_load_dwordx4 v[46:49], v[246:247], off offset:2048
	s_and_saveexec_b64 s[72:73], s[64:65]
	s_cbranch_execz .LBB0_434
	v_add_u32_e32 v2, s33, v1
	v_ashrrev_i32_e32 v3, 31, v2
	v_readlane_b32 s64, v249, 52
	v_lshlrev_b64 v[2:3], 6, v[2:3]
	v_readlane_b32 s65, v249, 53
	s_nop 1
	v_lshl_add_u64 v[14:15], s[64:65], 0, v[2:3]
	global_load_dwordx4 v[2:5], v[14:15], off
	global_load_dwordx4 v[6:9], v[14:15], off offset:16
	global_load_dwordx4 v[10:13], v[14:15], off offset:32
	s_nop 0
	global_load_dwordx4 v[14:17], v[14:15], off offset:48
	s_waitcnt vmcnt(0)
	v_mov_b32_e32 v18, v3
	v_mov_b32_e32 v19, v4
	v_mov_b32_e32 v3, v5
	v_mov_b32_e32 v4, v7
	v_mov_b32_e32 v5, v8
	v_mov_b32_e32 v7, v9
	v_pk_add_f32 v[2:3], v[18:19], v[2:3]
	v_pk_add_f32 v[4:5], v[4:5], v[6:7]
	v_pk_add_f32 v[2:3], v[2:3], v[2:3] op_sel:[0,1] op_sel_hi:[1,0]
	v_pk_add_f32 v[4:5], v[4:5], v[4:5] op_sel:[0,1] op_sel_hi:[1,0]
	v_add_f32_e32 v8, v10, v11
	v_add_f32_e32 v10, v12, v13
	v_mov_b32_e32 v9, v16
	v_mov_b32_e32 v11, v17
	v_mov_b32_e32 v3, v14
	v_mov_b32_e32 v5, v15
	v_pk_add_f32 v[2:3], v[2:3], v[4:5]
	v_pk_add_f32 v[4:5], v[8:9], v[10:11]
	s_nop 0
	v_pk_add_f32 v[2:3], v[2:3], v[4:5]
	s_nop 0
	v_add_f32_e32 v2, v2, v3
	v_fmamk_f32 v2, v2, 0x3a800000, v149
	v_rsq_f32_e32 v2, v2
	ds_write_b32 v140, v2
.LBB0_434:
	s_or_b64 exec, exec, s[72:73]
	s_and_b32 s72, s89, 1
	s_or_b32 s74, s72, s88
	s_and_b32 s75, s93, 7
	s_and_b64 s[72:73], s[2:3], exec
	s_cselect_b32 s72, s74, s75
	s_ashr_i32 s73, s72, 31
	s_lshl_b64 s[74:75], s[72:73], 16
	v_lshl_add_u64 v[22:23], v[114:115], 0, s[74:75]
	v_lshl_add_u64 v[2:3], v[116:117], 2, v[22:23]
	s_waitcnt vmcnt(0) lgkmcnt(0)
	s_barrier
	v_lshl_add_u64 v[6:7], v[122:123], 2, v[22:23]
	v_lshl_add_u64 v[2:3], v[118:119], 2, v[22:23]
	ds_read_b128 v[18:21], v147
	v_readlane_b32 s64, v249, 58
	v_readlane_b32 s65, v249, 59
	v_or_b32_e32 v24, s33, v141
	v_ashrrev_i32_e32 v25, 31, v24
	v_lshlrev_b64 v[24:25], 12, v[24:25]
	s_lshl_b32 s96, s72, 7
	v_lshl_add_u64 v[24:25], s[80:81], 0, v[24:25]
	s_ashr_i32 s97, s96, 31
	v_lshl_add_u64 v[26:27], s[96:97], 1, v[24:25]
	s_andn2_b64 vcc, exec, s[86:87]
	s_waitcnt vmcnt(2) lgkmcnt(0)
	v_mul_f32_e32 v10, v72, v18
	v_cndmask_b32_e64 v10, v10, 0, s[64:65]
	v_readlane_b32 s64, v249, 60
	v_mul_f32_e32 v12, v74, v20
	v_readlane_b32 s65, v249, 61
	v_mul_f32_e32 v11, v73, v19
	v_mul_f32_e32 v13, v75, v21
	v_cndmask_b32_e64 v12, v12, 0, s[64:65]
	v_readlane_b32 s64, v249, 62
	v_readlane_b32 s65, v249, 63
	v_cndmask_b32_e64 v13, v13, 0, s[12:13]
	v_and_b32_sdwa v20, v13, v166 dst_sel:DWORD dst_unused:UNUSED_PAD src0_sel:WORD_1 src1_sel:DWORD
	v_cndmask_b32_e64 v11, 0, v11, s[64:65]
	v_and_b32_sdwa v21, v11, v166 dst_sel:DWORD dst_unused:UNUSED_PAD src0_sel:WORD_1 src1_sel:DWORD
	v_and_b32_sdwa v18, v12, v166 dst_sel:DWORD dst_unused:UNUSED_PAD src0_sel:WORD_1 src1_sel:DWORD
	v_and_b32_sdwa v19, v10, v166 dst_sel:DWORD dst_unused:UNUSED_PAD src0_sel:WORD_1 src1_sel:DWORD
	v_add3_u32 v13, v13, v20, s92
	v_add3_u32 v11, v11, v21, s92
	v_add3_u32 v10, v10, v19, s92
	v_add3_u32 v12, v12, v18, s92
	v_and_b32_e32 v13, 0xffff0000, v13
	v_and_b32_e32 v18, 0xffff0000, v11
	v_or_b32_sdwa v11, v13, v12 dst_sel:DWORD dst_unused:UNUSED_PAD src0_sel:DWORD src1_sel:WORD_1
	v_or_b32_sdwa v10, v18, v10 dst_sel:DWORD dst_unused:UNUSED_PAD src0_sel:DWORD src1_sel:WORD_1
	ds_write_b64 v150, v[10:11]
	v_lshl_add_u64 v[10:11], v[124:125], 2, v[22:23]
	v_lshl_add_u64 v[2:3], v[120:121], 2, v[22:23]
	ds_read_b128 v[18:21], v147
	s_waitcnt vmcnt(2) lgkmcnt(0)
	v_mul_f32_e32 v15, v81, v19
	v_mul_f32_e32 v17, v83, v21
	v_mul_f32_e32 v16, v82, v20
	v_mul_f32_e32 v14, v80, v18
	v_cndmask_b32_e64 v15, 0, v15, s[18:19]
	v_cndmask_b32_e64 v17, v17, 0, s[20:21]
	v_cndmask_b32_e64 v14, v14, 0, s[14:15]
	v_cndmask_b32_e64 v16, v16, 0, s[16:17]
	v_and_b32_sdwa v20, v17, v166 dst_sel:DWORD dst_unused:UNUSED_PAD src0_sel:WORD_1 src1_sel:DWORD
	v_and_b32_sdwa v21, v15, v166 dst_sel:DWORD dst_unused:UNUSED_PAD src0_sel:WORD_1 src1_sel:DWORD
	v_and_b32_sdwa v18, v16, v166 dst_sel:DWORD dst_unused:UNUSED_PAD src0_sel:WORD_1 src1_sel:DWORD
	v_and_b32_sdwa v19, v14, v166 dst_sel:DWORD dst_unused:UNUSED_PAD src0_sel:WORD_1 src1_sel:DWORD
	v_add3_u32 v17, v17, v20, s92
	v_add3_u32 v15, v15, v21, s92
	v_add3_u32 v14, v14, v19, s92
	v_add3_u32 v16, v16, v18, s92
	v_and_b32_e32 v17, 0xffff0000, v17
	v_and_b32_e32 v18, 0xffff0000, v15
	v_or_b32_sdwa v15, v17, v16 dst_sel:DWORD dst_unused:UNUSED_PAD src0_sel:DWORD src1_sel:WORD_1
	v_or_b32_sdwa v14, v18, v14 dst_sel:DWORD dst_unused:UNUSED_PAD src0_sel:DWORD src1_sel:WORD_1
	ds_write_b64 v151, v[14:15]
	v_lshl_add_u64 v[14:15], v[126:127], 2, v[22:23]
	ds_read_b128 v[18:21], v147
	s_waitcnt vmcnt(1) lgkmcnt(0)
	v_mul_f32_e32 v3, v89, v19
	v_mul_f32_e32 v5, v91, v21
	v_mul_f32_e32 v4, v90, v20
	v_mul_f32_e32 v2, v88, v18
	v_cndmask_b32_e64 v3, 0, v3, s[26:27]
	v_cndmask_b32_e64 v5, v5, 0, s[28:29]
	v_cndmask_b32_e64 v2, v2, 0, s[22:23]
	v_cndmask_b32_e64 v4, v4, 0, s[24:25]
	v_and_b32_sdwa v20, v5, v166 dst_sel:DWORD dst_unused:UNUSED_PAD src0_sel:WORD_1 src1_sel:DWORD
	v_and_b32_sdwa v21, v3, v166 dst_sel:DWORD dst_unused:UNUSED_PAD src0_sel:WORD_1 src1_sel:DWORD
	v_and_b32_sdwa v18, v4, v166 dst_sel:DWORD dst_unused:UNUSED_PAD src0_sel:WORD_1 src1_sel:DWORD
	v_and_b32_sdwa v19, v2, v166 dst_sel:DWORD dst_unused:UNUSED_PAD src0_sel:WORD_1 src1_sel:DWORD
	v_add3_u32 v5, v5, v20, s92
	v_add3_u32 v3, v3, v21, s92
	v_add3_u32 v2, v2, v19, s92
	v_add3_u32 v4, v4, v18, s92
	v_and_b32_e32 v5, 0xffff0000, v5
	v_and_b32_e32 v18, 0xffff0000, v3
	v_or_b32_sdwa v3, v5, v4 dst_sel:DWORD dst_unused:UNUSED_PAD src0_sel:DWORD src1_sel:WORD_1
	v_or_b32_sdwa v2, v18, v2 dst_sel:DWORD dst_unused:UNUSED_PAD src0_sel:DWORD src1_sel:WORD_1
	ds_write_b64 v152, v[2:3]
	ds_read_b128 v[18:21], v147
	v_lshl_add_u64 v[2:3], v[128:129], 2, v[22:23]
	s_waitcnt lgkmcnt(0)
	v_mul_f32_e32 v7, v77, v19
	v_mul_f32_e32 v9, v79, v21
	v_mul_f32_e32 v8, v78, v20
	v_mul_f32_e32 v6, v76, v18
	v_cndmask_b32_e64 v7, 0, v7, s[36:37]
	v_cndmask_b32_e64 v9, v9, 0, s[38:39]
	v_cndmask_b32_e64 v6, v6, 0, s[30:31]
	v_cndmask_b32_e64 v8, v8, 0, s[34:35]
	v_and_b32_sdwa v20, v9, v166 dst_sel:DWORD dst_unused:UNUSED_PAD src0_sel:WORD_1 src1_sel:DWORD
	v_and_b32_sdwa v21, v7, v166 dst_sel:DWORD dst_unused:UNUSED_PAD src0_sel:WORD_1 src1_sel:DWORD
	v_and_b32_sdwa v18, v8, v166 dst_sel:DWORD dst_unused:UNUSED_PAD src0_sel:WORD_1 src1_sel:DWORD
	v_and_b32_sdwa v19, v6, v166 dst_sel:DWORD dst_unused:UNUSED_PAD src0_sel:WORD_1 src1_sel:DWORD
	v_add3_u32 v9, v9, v20, s92
	v_add3_u32 v7, v7, v21, s92
	v_add3_u32 v6, v6, v19, s92
	v_add3_u32 v8, v8, v18, s92
	v_and_b32_e32 v9, 0xffff0000, v9
	v_and_b32_e32 v18, 0xffff0000, v7
	v_or_b32_sdwa v7, v9, v8 dst_sel:DWORD dst_unused:UNUSED_PAD src0_sel:DWORD src1_sel:WORD_1
	v_or_b32_sdwa v6, v18, v6 dst_sel:DWORD dst_unused:UNUSED_PAD src0_sel:DWORD src1_sel:WORD_1
	ds_write_b64 v153, v[6:7]
	ds_read_b128 v[18:21], v147
	v_lshl_add_u64 v[6:7], v[130:131], 2, v[22:23]
	s_waitcnt lgkmcnt(0)
	v_mul_f32_e32 v11, v85, v19
	v_mul_f32_e32 v13, v87, v21
	v_mul_f32_e32 v12, v86, v20
	v_mul_f32_e32 v10, v84, v18
	v_cndmask_b32_e64 v11, 0, v11, s[44:45]
	v_cndmask_b32_e64 v13, v13, 0, s[46:47]
	v_cndmask_b32_e64 v10, v10, 0, s[40:41]
	v_cndmask_b32_e64 v12, v12, 0, s[42:43]
	v_and_b32_sdwa v20, v13, v166 dst_sel:DWORD dst_unused:UNUSED_PAD src0_sel:WORD_1 src1_sel:DWORD
	v_and_b32_sdwa v21, v11, v166 dst_sel:DWORD dst_unused:UNUSED_PAD src0_sel:WORD_1 src1_sel:DWORD
	v_and_b32_sdwa v18, v12, v166 dst_sel:DWORD dst_unused:UNUSED_PAD src0_sel:WORD_1 src1_sel:DWORD
	v_and_b32_sdwa v19, v10, v166 dst_sel:DWORD dst_unused:UNUSED_PAD src0_sel:WORD_1 src1_sel:DWORD
	v_add3_u32 v13, v13, v20, s92
	v_add3_u32 v11, v11, v21, s92
	v_add3_u32 v10, v10, v19, s92
	v_add3_u32 v12, v12, v18, s92
	v_and_b32_e32 v13, 0xffff0000, v13
	v_and_b32_e32 v18, 0xffff0000, v11
	v_or_b32_sdwa v11, v13, v12 dst_sel:DWORD dst_unused:UNUSED_PAD src0_sel:DWORD src1_sel:WORD_1
	v_or_b32_sdwa v10, v18, v10 dst_sel:DWORD dst_unused:UNUSED_PAD src0_sel:DWORD src1_sel:WORD_1
	v_lshl_add_u64 v[18:19], v[132:133], 1, v[26:27]
	ds_write_b64 v154, v[10:11]
	ds_read_b128 v[10:13], v147
	s_waitcnt vmcnt(3) lgkmcnt(0)
	v_mul_f32_e32 v22, v93, v11
	v_mul_f32_e32 v11, v94, v12
	v_mul_f32_e32 v10, v92, v10
	v_cndmask_b32_e64 v12, v10, 0, s[48:49]
	v_cndmask_b32_e64 v23, v11, 0, s[50:51]
	v_lshl_add_u64 v[10:11], v[134:135], 1, v[26:27]
	v_mul_f32_e32 v13, v95, v13
	v_and_b32_sdwa v10, v23, v166 dst_sel:DWORD dst_unused:UNUSED_PAD src0_sel:WORD_1 src1_sel:DWORD
	v_and_b32_sdwa v11, v12, v166 dst_sel:DWORD dst_unused:UNUSED_PAD src0_sel:WORD_1 src1_sel:DWORD
	v_add3_u32 v29, v12, v11, s92
	v_add3_u32 v30, v23, v10, s92
	v_lshl_add_u64 v[10:11], v[136:137], 1, v[26:27]
	v_cndmask_b32_e64 v28, 0, v22, s[52:53]
	v_cndmask_b32_e64 v13, v13, 0, s[54:55]
	v_and_b32_sdwa v10, v13, v166 dst_sel:DWORD dst_unused:UNUSED_PAD src0_sel:WORD_1 src1_sel:DWORD
	v_and_b32_sdwa v11, v28, v166 dst_sel:DWORD dst_unused:UNUSED_PAD src0_sel:WORD_1 src1_sel:DWORD
	v_add3_u32 v10, v13, v10, s92
	v_add3_u32 v11, v28, v11, s92
	v_and_b32_e32 v28, 0xffff0000, v10
	v_and_b32_e32 v31, 0xffff0000, v11
	v_lshl_add_u64 v[10:11], v[138:139], 1, v[26:27]
	v_or_b32_sdwa v27, v28, v30 dst_sel:DWORD dst_unused:UNUSED_PAD src0_sel:DWORD src1_sel:WORD_1
	v_or_b32_sdwa v26, v31, v29 dst_sel:DWORD dst_unused:UNUSED_PAD src0_sel:DWORD src1_sel:WORD_1
	ds_write_b64 v155, v[26:27]
	ds_read_b128 v[26:29], v147
	s_waitcnt vmcnt(5) lgkmcnt(0)
	v_mul_f32_e32 v4, v98, v28
	v_mul_f32_e32 v2, v96, v26
	v_mul_f32_e32 v3, v97, v27
	v_mul_f32_e32 v5, v99, v29
	v_cndmask_b32_e64 v2, v2, 0, s[56:57]
	v_cndmask_b32_e64 v4, v4, 0, s[58:59]
	v_cndmask_b32_e64 v3, 0, v3, s[60:61]
	v_cndmask_b32_e64 v5, v5, 0, s[62:63]
	v_and_b32_sdwa v26, v4, v166 dst_sel:DWORD dst_unused:UNUSED_PAD src0_sel:WORD_1 src1_sel:DWORD
	v_and_b32_sdwa v27, v2, v166 dst_sel:DWORD dst_unused:UNUSED_PAD src0_sel:WORD_1 src1_sel:DWORD
	v_add3_u32 v2, v2, v27, s92
	v_add3_u32 v4, v4, v26, s92
	v_and_b32_sdwa v26, v5, v166 dst_sel:DWORD dst_unused:UNUSED_PAD src0_sel:WORD_1 src1_sel:DWORD
	v_and_b32_sdwa v27, v3, v166 dst_sel:DWORD dst_unused:UNUSED_PAD src0_sel:WORD_1 src1_sel:DWORD
	v_add3_u32 v5, v5, v26, s92
	v_add3_u32 v3, v3, v27, s92
	v_and_b32_e32 v5, 0xffff0000, v5
	v_and_b32_e32 v26, 0xffff0000, v3
	v_or_b32_sdwa v3, v5, v4 dst_sel:DWORD dst_unused:UNUSED_PAD src0_sel:DWORD src1_sel:WORD_1
	v_or_b32_sdwa v2, v26, v2 dst_sel:DWORD dst_unused:UNUSED_PAD src0_sel:DWORD src1_sel:WORD_1
	ds_write_b64 v156, v[2:3]
	ds_read_b128 v[2:5], v147
	s_waitcnt vmcnt(4) lgkmcnt(0)
	v_mul_f32_e32 v4, v102, v4
	v_mul_f32_e32 v2, v100, v2
	v_mul_f32_e32 v3, v101, v3
	v_mul_f32_e32 v5, v103, v5
	v_cndmask_b32_e64 v2, v2, 0, s[4:5]
	v_cndmask_b32_e64 v4, v4, 0, s[6:7]
	v_cndmask_b32_e64 v3, 0, v3, s[8:9]
	v_cndmask_b32_e64 v5, v5, 0, s[10:11]
	v_and_b32_sdwa v6, v4, v166 dst_sel:DWORD dst_unused:UNUSED_PAD src0_sel:WORD_1 src1_sel:DWORD
	v_and_b32_sdwa v7, v2, v166 dst_sel:DWORD dst_unused:UNUSED_PAD src0_sel:WORD_1 src1_sel:DWORD
	v_add3_u32 v2, v2, v7, s92
	v_add3_u32 v4, v4, v6, s92
	v_and_b32_sdwa v6, v5, v166 dst_sel:DWORD dst_unused:UNUSED_PAD src0_sel:WORD_1 src1_sel:DWORD
	v_and_b32_sdwa v7, v3, v166 dst_sel:DWORD dst_unused:UNUSED_PAD src0_sel:WORD_1 src1_sel:DWORD
	v_add3_u32 v5, v5, v6, s92
	v_add3_u32 v3, v3, v7, s92
	v_and_b32_e32 v5, 0xffff0000, v5
	v_and_b32_e32 v6, 0xffff0000, v3
	v_or_b32_sdwa v3, v5, v4 dst_sel:DWORD dst_unused:UNUSED_PAD src0_sel:DWORD src1_sel:WORD_1
	v_or_b32_sdwa v2, v6, v2 dst_sel:DWORD dst_unused:UNUSED_PAD src0_sel:DWORD src1_sel:WORD_1
	ds_write_b64 v157, v[2:3]
	s_waitcnt vmcnt(3)
	ds_write_b16 v158, v34 offset:34816
	ds_write_b16_d16_hi v158, v34 offset:35088
	ds_write_b16 v158, v35 offset:35360
	ds_write_b16_d16_hi v158, v35 offset:35632
	ds_write_b16 v158, v36 offset:35904
	ds_write_b16_d16_hi v158, v36 offset:36176
	ds_write_b16 v158, v37 offset:36448
	ds_write_b16_d16_hi v159, v37 offset:34816
	s_waitcnt vmcnt(2)
	ds_write_b16 v160, v38 offset:34816
	ds_write_b16_d16_hi v160, v38 offset:35088
	ds_write_b16 v160, v39 offset:35360
	ds_write_b16_d16_hi v160, v39 offset:35632
	ds_write_b16 v160, v40 offset:35904
	ds_write_b16_d16_hi v160, v40 offset:36176
	ds_write_b16 v160, v41 offset:36448
	ds_write_b16_d16_hi v161, v41 offset:34816
	s_waitcnt vmcnt(1)
	ds_write_b16 v162, v42 offset:34816
	ds_write_b16_d16_hi v162, v42 offset:35088
	ds_write_b16 v162, v43 offset:35360
	ds_write_b16_d16_hi v162, v43 offset:35632
	ds_write_b16 v162, v44 offset:35904
	ds_write_b16_d16_hi v162, v44 offset:36176
	ds_write_b16 v162, v45 offset:36448
	ds_write_b16_d16_hi v163, v45 offset:34816
	s_waitcnt vmcnt(0)
	ds_write_b16 v164, v46 offset:34816
	ds_write_b16_d16_hi v164, v46 offset:35088
	ds_write_b16 v164, v47 offset:35360
	ds_write_b16_d16_hi v164, v47 offset:35632
	ds_write_b16 v164, v48 offset:35904
	ds_write_b16_d16_hi v164, v48 offset:36176
	ds_write_b16 v164, v49 offset:36448
	ds_write_b16_d16_hi v165, v49 offset:34816
	v_cndmask_b32_e64 v2, 0, 1, s[86:87]
	v_cmp_ne_u32_e64 s[74:75], 1, v2
	s_waitcnt lgkmcnt(0)
	s_barrier
	v_readlane_b32 s98, v249, 24
	v_readlane_b32 s99, v249, 25
	v_readlane_b32 s100, v249, 20
	v_readlane_b32 s101, v249, 21
	v_add_u32_e32 v244, s96, v142
	v_lshlrev_b32_e32 v244, 2, v244
	v_or_b32_e32 v245, s96, v146
	v_lshlrev_b32_e32 v246, 2, v245
	v_add_u32_e32 v247, s33, v142
	v_lshlrev_b32_e32 v247, 12, v247
	v_lshl_add_u32 v247, v245, 1, v247
	global_load_dword v248, v244, s[98:99]
	global_load_dwordx4 v[180:183], v246, s[100:101]
	global_load_dwordx4 v[184:187], v246, s[100:101] offset:64
	global_load_dwordx4 v[188:191], v246, s[100:101] offset:128
	global_load_dwordx4 v[192:195], v246, s[100:101] offset:192
	global_load_dwordx4 v[196:199], v246, s[100:101] offset:256
	global_load_dwordx4 v[200:203], v246, s[100:101] offset:320
	global_load_dwordx4 v[204:207], v246, s[100:101] offset:384
	global_load_dwordx4 v[208:211], v246, s[100:101] offset:448
	global_load_dwordx2 v[212:213], v247, s[80:81]
	global_load_dwordx2 v[214:215], v247, s[80:81] offset:32
	global_load_dwordx2 v[216:217], v247, s[80:81] offset:64
	global_load_dwordx2 v[218:219], v247, s[80:81] offset:96
	global_load_dwordx2 v[220:221], v247, s[80:81] offset:128
	global_load_dwordx2 v[222:223], v247, s[80:81] offset:160
	global_load_dwordx2 v[224:225], v247, s[80:81] offset:192
	global_load_dwordx2 v[226:227], v247, s[80:81] offset:224
	v_readfirstlane_b32 s98, v178
	v_add_u32_e32 v70, v143, v144
	v_add_u32_e32 v71, v145, v148
	s_lshr_b32 s98, s98, 7
	s_add_i32 s98, s98, 1
	v_mov_b32_e32 v2, 0
	v_mov_b32_e32 v3, 0
	v_mov_b32_e32 v4, 0
	v_mov_b32_e32 v5, 0
	v_mov_b32_e32 v6, 0
	v_mov_b32_e32 v7, 0
	v_mov_b32_e32 v8, 0
	v_mov_b32_e32 v9, 0
	v_mov_b32_e32 v10, 0
	v_mov_b32_e32 v11, 0
	v_mov_b32_e32 v12, 0
	v_mov_b32_e32 v13, 0
	v_mov_b32_e32 v14, 0
	v_mov_b32_e32 v15, 0
	v_mov_b32_e32 v16, 0
	v_mov_b32_e32 v17, 0
	v_mov_b32_e32 v18, 0
	v_mov_b32_e32 v19, 0
	v_mov_b32_e32 v20, 0
	v_mov_b32_e32 v21, 0
	v_mov_b32_e32 v22, 0
	v_mov_b32_e32 v23, 0
	v_mov_b32_e32 v24, 0
	v_mov_b32_e32 v25, 0
	v_mov_b32_e32 v26, 0
	v_mov_b32_e32 v27, 0
	v_mov_b32_e32 v28, 0
	v_mov_b32_e32 v29, 0
	v_mov_b32_e32 v30, 0
	v_mov_b32_e32 v31, 0
	v_mov_b32_e32 v32, 0
	v_mov_b32_e32 v33, 0
	ds_read_b128 v[66:69], v70
	ds_read_b128 v[34:37], v71 offset:34816
	ds_read_b128 v[38:41], v71 offset:39168
	ds_read_b128 v[42:45], v71 offset:43520
	ds_read_b128 v[46:49], v71 offset:47872
	ds_read_b128 v[50:53], v71 offset:52224
	ds_read_b128 v[54:57], v71 offset:56576
	ds_read_b128 v[58:61], v71 offset:60928
	ds_read_b128 v[62:65], v71 offset:65280
	s_waitcnt lgkmcnt(0)
	v_mfma_f32_16x16x32_bf16 v[2:5], v[34:37], v[66:69], v[2:5]
	v_mfma_f32_16x16x32_bf16 v[6:9], v[38:41], v[66:69], v[6:9]
	v_mfma_f32_16x16x32_bf16 v[10:13], v[42:45], v[66:69], v[10:13]
	v_mfma_f32_16x16x32_bf16 v[14:17], v[46:49], v[66:69], v[14:17]
	v_mfma_f32_16x16x32_bf16 v[18:21], v[50:53], v[66:69], v[18:21]
	v_mfma_f32_16x16x32_bf16 v[22:25], v[54:57], v[66:69], v[22:25]
	v_mfma_f32_16x16x32_bf16 v[26:29], v[58:61], v[66:69], v[26:29]
	v_mfma_f32_16x16x32_bf16 v[30:33], v[62:65], v[66:69], v[30:33]
	s_cmp_lt_u32 s98, 2
	s_cbranch_scc1 .Lsgu_mm_done
	ds_read_b128 v[104:107], v70 offset:64
	ds_read_b128 v[72:75], v71 offset:34880
	ds_read_b128 v[76:79], v71 offset:39232
	ds_read_b128 v[80:83], v71 offset:43584
	ds_read_b128 v[84:87], v71 offset:47936
	ds_read_b128 v[88:91], v71 offset:52288
	ds_read_b128 v[92:95], v71 offset:56640
	ds_read_b128 v[96:99], v71 offset:60992
	ds_read_b128 v[100:103], v71 offset:65344
	s_waitcnt lgkmcnt(0)
	v_mfma_f32_16x16x32_bf16 v[2:5], v[72:75], v[104:107], v[2:5]
	v_mfma_f32_16x16x32_bf16 v[6:9], v[76:79], v[104:107], v[6:9]
	v_mfma_f32_16x16x32_bf16 v[10:13], v[80:83], v[104:107], v[10:13]
	v_mfma_f32_16x16x32_bf16 v[14:17], v[84:87], v[104:107], v[14:17]
	v_mfma_f32_16x16x32_bf16 v[18:21], v[88:91], v[104:107], v[18:21]
	v_mfma_f32_16x16x32_bf16 v[22:25], v[92:95], v[104:107], v[22:25]
	v_mfma_f32_16x16x32_bf16 v[26:29], v[96:99], v[104:107], v[26:29]
	v_mfma_f32_16x16x32_bf16 v[30:33], v[100:103], v[104:107], v[30:33]
	s_cmp_lt_u32 s98, 3
	s_cbranch_scc1 .Lsgu_mm_done
	ds_read_b128 v[66:69], v70 offset:128
	ds_read_b128 v[34:37], v71 offset:34944
	ds_read_b128 v[38:41], v71 offset:39296
	ds_read_b128 v[42:45], v71 offset:43648
	ds_read_b128 v[46:49], v71 offset:48000
	ds_read_b128 v[50:53], v71 offset:52352
	ds_read_b128 v[54:57], v71 offset:56704
	ds_read_b128 v[58:61], v71 offset:61056
	ds_read_b128 v[62:65], v71 offset:65408
	s_waitcnt lgkmcnt(0)
	v_mfma_f32_16x16x32_bf16 v[2:5], v[34:37], v[66:69], v[2:5]
	v_mfma_f32_16x16x32_bf16 v[6:9], v[38:41], v[66:69], v[6:9]
	v_mfma_f32_16x16x32_bf16 v[10:13], v[42:45], v[66:69], v[10:13]
	v_mfma_f32_16x16x32_bf16 v[14:17], v[46:49], v[66:69], v[14:17]
	v_mfma_f32_16x16x32_bf16 v[18:21], v[50:53], v[66:69], v[18:21]
	v_mfma_f32_16x16x32_bf16 v[22:25], v[54:57], v[66:69], v[22:25]
	v_mfma_f32_16x16x32_bf16 v[26:29], v[58:61], v[66:69], v[26:29]
	v_mfma_f32_16x16x32_bf16 v[30:33], v[62:65], v[66:69], v[30:33]
	s_cmp_lt_u32 s98, 4
	s_cbranch_scc1 .Lsgu_mm_done
	ds_read_b128 v[104:107], v70 offset:192
	ds_read_b128 v[72:75], v71 offset:35008
	ds_read_b128 v[76:79], v71 offset:39360
	ds_read_b128 v[80:83], v71 offset:43712
	ds_read_b128 v[84:87], v71 offset:48064
	ds_read_b128 v[88:91], v71 offset:52416
	ds_read_b128 v[92:95], v71 offset:56768
	ds_read_b128 v[96:99], v71 offset:61120
	ds_read_b128 v[100:103], v71 offset:65472
	s_waitcnt lgkmcnt(0)
	v_mfma_f32_16x16x32_bf16 v[2:5], v[72:75], v[104:107], v[2:5]
	v_mfma_f32_16x16x32_bf16 v[6:9], v[76:79], v[104:107], v[6:9]
	v_mfma_f32_16x16x32_bf16 v[10:13], v[80:83], v[104:107], v[10:13]
	v_mfma_f32_16x16x32_bf16 v[14:17], v[84:87], v[104:107], v[14:17]
	v_mfma_f32_16x16x32_bf16 v[18:21], v[88:91], v[104:107], v[18:21]
	v_mfma_f32_16x16x32_bf16 v[22:25], v[92:95], v[104:107], v[22:25]
	v_mfma_f32_16x16x32_bf16 v[26:29], v[96:99], v[104:107], v[26:29]
	v_mfma_f32_16x16x32_bf16 v[30:33], v[100:103], v[104:107], v[30:33]
